# dt fold: dt-carrying tile of row-tile group g is column tile g mod 3, so the extra work lands on 24 different workgroups per XCD instead of 8
# speedup vs baseline: 1.0044x; 1.0044x over previous
.LBB0_397:
	v_readlane_b32 s56, v244, 0
	v_readlane_b32 s57, v244, 1
	v_readlane_b32 s58, v244, 2
	v_readlane_b32 s59, v244, 3
	v_readlane_b32 s60, v244, 4
	v_readlane_b32 s61, v244, 5
	s_ashr_i32 s25, s24, 31
	v_readlane_b32 s62, v244, 6
	v_readlane_b32 s63, v244, 7
	s_mov_b64 s[56:57], s[60:61]
	s_lshl_b64 s[26:27], s[24:25], 19
	s_mov_b64 s[58:59], s[62:63]
	s_add_u32 s26, s58, s26
	s_addc_u32 s27, s59, s27
	s_and_b64 s[28:29], s[0:1], exec
	s_cselect_b32 s5, s27, s31
	s_cselect_b32 s8, s26, s30
	s_ashr_i32 s19, s18, 31
	s_lshl_b64 s[28:29], s[18:19], 19
	s_add_u32 s28, s33, s28
	s_addc_u32 s29, s38, s29
	s_and_b64 s[36:37], s[0:1], exec
	s_cselect_b32 s19, s29, s35
	s_cselect_b32 s25, s28, s34
	s_add_u32 s30, s30, 0x40080
	s_addc_u32 s31, s31, 0
	s_add_u32 s53, s34, 0x100
	v_mov_b32_e32 v0, 0
	s_addc_u32 s54, s35, 0
	s_mov_b32 s55, -2
	v_mov_b32_e32 v1, v0
	v_mov_b32_e32 v2, v0
	v_mov_b32_e32 v3, v0
	v_mov_b32_e32 v4, v0
	v_mov_b32_e32 v5, v0
	v_mov_b32_e32 v6, v0
	v_mov_b32_e32 v7, v0
	v_mov_b32_e32 v16, v0
	v_mov_b32_e32 v17, v0
	v_mov_b32_e32 v18, v0
	v_mov_b32_e32 v19, v0
	v_mov_b32_e32 v20, v0
	v_mov_b32_e32 v21, v0
	v_mov_b32_e32 v22, v0
	v_mov_b32_e32 v23, v0
	v_mov_b32_e32 v32, v0
	v_mov_b32_e32 v33, v0
	v_mov_b32_e32 v34, v0
	v_mov_b32_e32 v35, v0
	v_mov_b32_e32 v36, v0
	v_mov_b32_e32 v37, v0
	v_mov_b32_e32 v38, v0
	v_mov_b32_e32 v39, v0
	v_mov_b32_e32 v48, v0
	v_mov_b32_e32 v49, v0
	v_mov_b32_e32 v50, v0
	v_mov_b32_e32 v51, v0
	v_mov_b32_e32 v52, v0
	v_mov_b32_e32 v53, v0
	v_mov_b32_e32 v54, v0
	v_mov_b32_e32 v55, v0
	v_mov_b32_e32 v8, v0
	v_mov_b32_e32 v9, v0
	v_mov_b32_e32 v10, v0
	v_mov_b32_e32 v11, v0
	v_mov_b32_e32 v12, v0
	v_mov_b32_e32 v13, v0
	v_mov_b32_e32 v14, v0
	v_mov_b32_e32 v15, v0
	v_mov_b32_e32 v24, v0
	v_mov_b32_e32 v25, v0
	v_mov_b32_e32 v26, v0
	v_mov_b32_e32 v27, v0
	v_mov_b32_e32 v28, v0
	v_mov_b32_e32 v29, v0
	v_mov_b32_e32 v30, v0
	v_mov_b32_e32 v31, v0
	v_mov_b32_e32 v40, v0
	v_mov_b32_e32 v41, v0
	v_mov_b32_e32 v42, v0
	v_mov_b32_e32 v43, v0
	v_mov_b32_e32 v44, v0
	v_mov_b32_e32 v45, v0
	v_mov_b32_e32 v46, v0
	v_mov_b32_e32 v47, v0
	v_mov_b32_e32 v56, v0
	v_mov_b32_e32 v57, v0
	v_mov_b32_e32 v58, v0
	v_mov_b32_e32 v59, v0
	v_mov_b32_e32 v60, v0
	v_mov_b32_e32 v61, v0
	v_mov_b32_e32 v62, v0
	v_mov_b32_e32 v63, v0
	v_mov_b32_e32 v64, v0
	v_mov_b32_e32 v65, v0
	v_mov_b32_e32 v66, v0
	v_mov_b32_e32 v67, v0
	v_mov_b32_e32 v68, v0
	v_mov_b32_e32 v69, v0
	v_mov_b32_e32 v70, v0
	v_mov_b32_e32 v71, v0
	v_mov_b32_e32 v80, v0
	v_mov_b32_e32 v81, v0
	v_mov_b32_e32 v82, v0
	v_mov_b32_e32 v83, v0
	v_mov_b32_e32 v84, v0
	v_mov_b32_e32 v85, v0
	v_mov_b32_e32 v86, v0
	v_mov_b32_e32 v87, v0
	v_mov_b32_e32 v96, v0
	v_mov_b32_e32 v97, v0
	v_mov_b32_e32 v98, v0
	v_mov_b32_e32 v99, v0
	v_mov_b32_e32 v100, v0
	v_mov_b32_e32 v101, v0
	v_mov_b32_e32 v102, v0
	v_mov_b32_e32 v103, v0
	v_mov_b32_e32 v112, v0
	v_mov_b32_e32 v113, v0
	v_mov_b32_e32 v114, v0
	v_mov_b32_e32 v115, v0
	v_mov_b32_e32 v116, v0
	v_mov_b32_e32 v117, v0
	v_mov_b32_e32 v118, v0
	v_mov_b32_e32 v119, v0
	v_mov_b32_e32 v72, v0
	v_mov_b32_e32 v73, v0
	v_mov_b32_e32 v74, v0
	v_mov_b32_e32 v75, v0
	v_mov_b32_e32 v76, v0
	v_mov_b32_e32 v77, v0
	v_mov_b32_e32 v78, v0
	v_mov_b32_e32 v79, v0
	v_mov_b32_e32 v88, v0
	v_mov_b32_e32 v89, v0
	v_mov_b32_e32 v90, v0
	v_mov_b32_e32 v91, v0
	v_mov_b32_e32 v92, v0
	v_mov_b32_e32 v93, v0
	v_mov_b32_e32 v94, v0
	v_mov_b32_e32 v95, v0
	v_mov_b32_e32 v104, v0
	v_mov_b32_e32 v105, v0
	v_mov_b32_e32 v106, v0
	v_mov_b32_e32 v107, v0
	v_mov_b32_e32 v108, v0
	v_mov_b32_e32 v109, v0
	v_mov_b32_e32 v110, v0
	v_mov_b32_e32 v111, v0
	v_mov_b32_e32 v120, v0
	v_mov_b32_e32 v121, v0
	v_mov_b32_e32 v122, v0
	v_mov_b32_e32 v123, v0
	v_mov_b32_e32 v124, v0
	v_mov_b32_e32 v125, v0
	v_mov_b32_e32 v126, v0
	v_mov_b32_e32 v127, v0
	s_lshr_b32 s98, s4, 3
	s_mul_i32 s99, s98, 0x5556
	s_lshr_b32 s99, s99, 16
	s_mul_i32 s99, s99, 3
	s_sub_u32 s98, s98, s99
	s_cmp_eq_u32 s6, s98
	s_cselect_b32 s84, 1, 0
	s_cbranch_scc0 .Ldtf_nosetup
	v_readfirstlane_b32 s85, v182
	s_bfe_u32 s85, s85, 0x20006
	v_readlane_b32 s98, v244, 6
	v_readlane_b32 s99, v244, 7
	s_add_u32 s100, s98, 0x1a000000
	s_addc_u32 s101, s99, 0
	s_add_u32 s98, s98, 0x18600000
	s_addc_u32 s99, s99, 0
	v_and_b32_e32 v245, 15, v182
	v_bfe_u32 v254, v182, 4, 2
	v_lshlrev_b32_e32 v245, 11, v245
	v_lshl_add_u32 v245, v254, 4, v245
	v_mov_b32_e32 v246, 0
	v_mov_b32_e32 v247, 0
	v_mov_b32_e32 v248, 0
	v_mov_b32_e32 v249, 0
	v_mov_b32_e32 v250, 0
	v_mov_b32_e32 v251, 0
	v_mov_b32_e32 v252, 0
	v_mov_b32_e32 v253, 0
	global_load_dwordx4 v[232:235], v245, s[98:99]
	global_load_dwordx4 v[236:239], v245, s[98:99] offset:64
	s_add_u32 s98, s98, 0x80
	s_addc_u32 s99, s99, 0
	s_waitcnt vmcnt(0)
	s_cmp_lt_u32 s85, 2
	s_cbranch_scc1 .Ldtf_d01
	s_cmp_eq_u32 s85, 2
	s_cbranch_scc1 .Ldtf_loop2
	s_branch .Ldtf_loop3
